# in-proj phase: the head-row partial-sum reduction (2 dependent load rounds before the GEMM) runs on the last 32 workgroups, which have one fewer GEMM tile, instead of the first 32 (critical path)
# baseline (speedup 1.0000x reference)
; __device__ __forceinline__ void reduce_hx(unsigned char* ws, const int tid, const int bx, const int G) {
;     const f32x4* part = (const f32x4*)(ws + WS_PART); f32x4* hx = (f32x4*)(ws + WS_HX);
;     for (int e = bx * NTHR + tid; e < 64 * 1024 / 4; e += G * NTHR) { f32x4 s = (f32x4){0.f, 0.f, 0.f, 0.f};
; #pragma unroll 16
;         for (int kc = 0; kc < 32; ++kc) s += part[(size_t)kc * 16384 + e];
;         hx[e] = s; }
; }
.LBB0_216:
	s_andn2_b64 vcc, exec, s[4:5]
	s_waitcnt lgkmcnt(0)
	s_mov_b64 s[8:9], 0
	s_cbranch_vccnz .LBB0_394
	s_cmp_gt_i32 s47, 0
	s_mov_b64 s[4:5], -1
	s_cbranch_scc0 .LBB0_392
	s_mov_b32 s10, s46
	s_mov_b32 s21, s37
	s_mov_b32 s6, s3
	s_mov_b32 s70, s2
	s_mov_b64 s[4:5], s[0:1]
	v_mbcnt_lo_u32_b32 v130, -1, 0
	v_mbcnt_hi_u32_b32 v130, -1, v130
	v_lshl_or_b32 v130, s6, 6, v130
	s_load_dwordx2 s[6:7], s[4:5], 0xb0
	s_sub_i32 s18, s21, 32
	s_max_i32 s18, s18, 0
	s_sub_i32 s18, s70, s18
	s_lshl_b32 s18, s18, 9
	v_add_u32_e32 v6, s18, v130
	s_movk_i32 s8, 0x4000
	v_cmp_gt_u32_e32 vcc, s8, v6
	v_ashrrev_i32_e32 v131, 31, v130
	s_and_saveexec_b64 s[8:9], vcc
	s_cbranch_execz .LBB0_223
	s_waitcnt lgkmcnt(0)
	s_add_u32 s12, s6, 0x40000
	s_addc_u32 s13, s7, 0
	s_lshl_b32 s14, s21, 9
	s_ashr_i32 s19, s18, 31
	v_lshl_add_u64 v[2:3], v[130:131], 0, s[18:19]
	s_ashr_i32 s15, s14, 31
	v_lshl_add_u64 v[8:9], v[2:3], 4, s[6:7]
	s_lshl_b64 s[18:19], s[14:15], 4
	s_mov_b64 s[22:23], 0
